# silu(c) staging loads batched; L2 tile: attention-output loads of the group norm hoisted above the LRU normalize loop
# speedup vs baseline: 1.0128x; 1.0008x over previous
.Ll2_tail:
	s_add_i32 s11, s11, -1
	v_subrev_u32_e32 v126, 64, v126
	s_cmp_eq_u32 s12, 8
	s_mov_b32 s14, s12
	s_cbranch_scc0 .Ll2_step
	s_waitcnt vmcnt(0)
	s_add_i32 s26, s10, s43
	s_ashr_i32 s27, s26, 31
	s_lshl_b64 s[28:29], s[26:27], 10
	v_readlane_b32 s76, v255, 54
	v_readlane_b32 s77, v255, 55
	v_lshrrev_b32_e32 v162, 4, v228
	v_and_b32_e32 v163, 15, v228
	v_lshlrev_b32_e32 v163, 4, v163
	s_add_u32 s76, s76, s28
	s_addc_u32 s77, s77, s29
	v_lshl_add_u32 v162, v162, 10, v163
	v_add_u32_e32 v163, 0x1000, v162
	global_load_dwordx4 v[130:133], v162, s[76:77]
	global_load_dwordx4 v[134:137], v162, s[76:77] offset:256
	global_load_dwordx4 v[138:141], v162, s[76:77] offset:512
	global_load_dwordx4 v[142:145], v162, s[76:77] offset:768
	global_load_dwordx4 v[146:149], v163, s[76:77]
	global_load_dwordx4 v[150:153], v163, s[76:77] offset:256
	global_load_dwordx4 v[154:157], v163, s[76:77] offset:512
	global_load_dwordx4 v[158:161], v163, s[76:77] offset:768

.LBB0_290:
	v_add_u32_e32 v5, s6, v0
	ds_read2st64_b32 v[8:9], v5 offset1:1
	ds_read2st64_b32 v[12:13], v6 offset1:1
	ds_read2st64_b32 v[14:15], v6 offset0:2 offset1:3
	s_add_i32 s6, s6, 64
	s_cmpk_lg_i32 s6, 0x100
	s_waitcnt lgkmcnt(2)
	v_add_f32_e32 v7, 0, v8
	v_add_f32_e32 v7, v7, v9
	ds_read2st64_b32 v[8:9], v5 offset0:2 offset1:3
	s_waitcnt lgkmcnt(0)
	v_add_f32_e32 v7, v7, v8
	v_add_f32_e32 v7, v7, v9
	ds_read2st64_b32 v[8:9], v5 offset0:4 offset1:5
	s_waitcnt lgkmcnt(0)
	v_add_f32_e32 v7, v7, v8
	v_add_f32_e32 v7, v7, v9
	ds_read2st64_b32 v[8:9], v5 offset0:6 offset1:7
	s_waitcnt lgkmcnt(0)
	v_add_f32_e32 v5, v7, v8
	v_add_f32_e32 v5, v5, v9
	v_fmamk_f32 v5, v5, 0x3b000000, v190
	v_cmp_gt_f32_e32 vcc, s96, v5
	v_mul_f32_e32 v7, 0x4b800000, v5
	s_nop 0
	v_cndmask_b32_e32 v5, v5, v7, vcc
	v_rsq_f32_e32 v5, v5
	s_nop 0
	v_mul_f32_e32 v7, 0x45800000, v5
	v_cndmask_b32_e32 v8, v5, v7, vcc
	v_ashrrev_i32_e32 v5, 31, v4
	v_lshlrev_b64 v[10:11], 11, v[4:5]
	v_pk_mul_f32 v[12:13], v[12:13], v[8:9] op_sel_hi:[1,0]
	v_pk_mul_f32 v[14:15], v[14:15], v[8:9] op_sel_hi:[1,0]
	v_lshl_add_u64 v[10:11], v[2:3], 0, v[10:11]
	v_cvt_pk_bf16_f32 v12, v12, v13
	v_cvt_pk_bf16_f32 v13, v14, v15
	global_store_dwordx2 v[10:11], v[12:13], off offset:1024
	ds_read2st64_b32 v[12:13], v6 offset0:4 offset1:5
	ds_read2st64_b32 v[14:15], v6 offset0:6 offset1:7
	v_add_u32_e32 v4, 16, v4
	s_waitcnt lgkmcnt(1)
	v_pk_mul_f32 v[12:13], v[12:13], v[8:9] op_sel_hi:[1,0]
	s_waitcnt lgkmcnt(0)
	v_pk_mul_f32 v[14:15], v[8:9], v[14:15] op_sel_hi:[0,1]
	v_cvt_pk_bf16_f32 v12, v12, v13
	v_cvt_pk_bf16_f32 v13, v14, v15
	global_store_dwordx2 v[10:11], v[12:13], off offset:1056
	ds_read2st64_b32 v[12:13], v6 offset0:8 offset1:9
	ds_read2st64_b32 v[14:15], v6 offset0:10 offset1:11
	s_waitcnt lgkmcnt(1)
	v_pk_mul_f32 v[12:13], v[8:9], v[12:13] op_sel_hi:[0,1]
	s_waitcnt lgkmcnt(0)
	v_pk_mul_f32 v[14:15], v[8:9], v[14:15] op_sel_hi:[0,1]
	v_cvt_pk_bf16_f32 v12, v12, v13
	v_cvt_pk_bf16_f32 v13, v14, v15
	global_store_dwordx2 v[10:11], v[12:13], off offset:1088
	ds_read2st64_b32 v[12:13], v6 offset0:12 offset1:13
	ds_read2st64_b32 v[14:15], v6 offset0:14 offset1:15
	v_add_u32_e32 v6, 0x1000, v6
	s_waitcnt lgkmcnt(1)
	v_pk_mul_f32 v[12:13], v[8:9], v[12:13] op_sel_hi:[0,1]
	s_waitcnt lgkmcnt(0)
	v_pk_mul_f32 v[8:9], v[8:9], v[14:15] op_sel_hi:[0,1]
	v_cvt_pk_bf16_f32 v12, v12, v13
	v_cvt_pk_bf16_f32 v13, v8, v9
	global_store_dwordx2 v[10:11], v[12:13], off offset:1120
	s_cbranch_scc1 .LBB0_290
	s_add_i32 s6, s10, s43
	s_ashr_i32 s7, s6, 31
	v_lshrrev_b32_e32 v2, 4, v228
	v_and_b32_e32 v3, 15, v228
	v_lshlrev_b32_e32 v3, 4, v3
	s_lshl_b64 s[6:7], s[6:7], 11
	v_lshl_add_u32 v5, v2, 11, v3
	s_add_u32 s6, s33, s6
	s_addc_u32 s7, s42, s7
	v_add_u32_e32 v7, 0x2000, v5
	s_mov_b32 s10, 0xffff0000
	s_waitcnt vmcnt(20)
	v_lshlrev_b32_e32 v40, 16, v130
	v_lshlrev_b32_e32 v41, 16, v131
	v_lshlrev_b32_e32 v42, 16, v132
	v_lshlrev_b32_e32 v43, 16, v133
	v_lshlrev_b32_e32 v44, 16, v134
	v_lshlrev_b32_e32 v45, 16, v135
	v_lshlrev_b32_e32 v46, 16, v136
	v_lshlrev_b32_e32 v47, 16, v137
	v_lshlrev_b32_e32 v48, 16, v138
	v_lshlrev_b32_e32 v49, 16, v139
	v_lshlrev_b32_e32 v50, 16, v140
	v_lshlrev_b32_e32 v51, 16, v141
	v_lshlrev_b32_e32 v52, 16, v142
	v_lshlrev_b32_e32 v53, 16, v143
	v_lshlrev_b32_e32 v54, 16, v144
	v_lshlrev_b32_e32 v55, 16, v145
	v_and_b32_e32 v130, s10, v130
	v_and_b32_e32 v131, s10, v131
	v_and_b32_e32 v132, s10, v132
	v_and_b32_e32 v133, s10, v133
	v_and_b32_e32 v134, s10, v134
	v_and_b32_e32 v135, s10, v135
	v_and_b32_e32 v136, s10, v136
	v_and_b32_e32 v137, s10, v137
	v_and_b32_e32 v138, s10, v138
	v_and_b32_e32 v139, s10, v139
	v_and_b32_e32 v140, s10, v140
	v_and_b32_e32 v141, s10, v141
	v_and_b32_e32 v142, s10, v142
	v_and_b32_e32 v143, s10, v143
	v_and_b32_e32 v144, s10, v144
	v_and_b32_e32 v145, s10, v145
	v_mul_f32_e32 v72, v40, v40
	v_mul_f32_e32 v73, v41, v41
	v_mul_f32_e32 v74, v42, v42
	v_mul_f32_e32 v75, v43, v43
	v_fmac_f32_e32 v72, v130, v130
	v_fmac_f32_e32 v73, v131, v131
	v_fmac_f32_e32 v74, v132, v132
	v_fmac_f32_e32 v75, v133, v133
	v_fmac_f32_e32 v72, v44, v44
	v_fmac_f32_e32 v73, v45, v45
	v_fmac_f32_e32 v74, v46, v46
	v_fmac_f32_e32 v75, v47, v47
	v_fmac_f32_e32 v72, v48, v48
	v_fmac_f32_e32 v73, v49, v49
	v_fmac_f32_e32 v74, v50, v50
	v_fmac_f32_e32 v75, v51, v51
	v_fmac_f32_e32 v72, v52, v52
	v_fmac_f32_e32 v73, v53, v53
	v_fmac_f32_e32 v74, v54, v54
	v_fmac_f32_e32 v75, v55, v55
	v_fmac_f32_e32 v72, v134, v134
	v_fmac_f32_e32 v73, v135, v135
	v_fmac_f32_e32 v74, v136, v136
	v_fmac_f32_e32 v75, v137, v137
	v_fmac_f32_e32 v72, v138, v138
	v_fmac_f32_e32 v73, v139, v139
	v_fmac_f32_e32 v74, v140, v140
	v_fmac_f32_e32 v75, v141, v141
	v_fmac_f32_e32 v72, v142, v142
	v_fmac_f32_e32 v73, v143, v143
	v_fmac_f32_e32 v74, v144, v144
	v_fmac_f32_e32 v75, v145, v145
	v_add_f32_e32 v72, v72, v73
	v_add_f32_e32 v74, v74, v75
	s_nop 0
	v_add_f32_e32 v72, v72, v74
	s_waitcnt vmcnt(16)
	v_lshlrev_b32_e32 v56, 16, v146
	v_lshlrev_b32_e32 v57, 16, v147
	v_lshlrev_b32_e32 v58, 16, v148
	v_lshlrev_b32_e32 v59, 16, v149
	v_lshlrev_b32_e32 v60, 16, v150
	v_lshlrev_b32_e32 v61, 16, v151
	v_lshlrev_b32_e32 v62, 16, v152
	v_lshlrev_b32_e32 v63, 16, v153
	v_lshlrev_b32_e32 v64, 16, v154
	v_lshlrev_b32_e32 v65, 16, v155
	v_lshlrev_b32_e32 v66, 16, v156
	v_lshlrev_b32_e32 v67, 16, v157
	v_lshlrev_b32_e32 v68, 16, v158
	v_lshlrev_b32_e32 v69, 16, v159
	v_lshlrev_b32_e32 v70, 16, v160
	v_lshlrev_b32_e32 v71, 16, v161
	v_and_b32_e32 v146, s10, v146
	v_and_b32_e32 v147, s10, v147
	v_and_b32_e32 v148, s10, v148
	v_and_b32_e32 v149, s10, v149
	v_and_b32_e32 v150, s10, v150
	v_and_b32_e32 v151, s10, v151
	v_and_b32_e32 v152, s10, v152
	v_and_b32_e32 v153, s10, v153
	v_and_b32_e32 v154, s10, v154
	v_and_b32_e32 v155, s10, v155
	v_and_b32_e32 v156, s10, v156
	v_and_b32_e32 v157, s10, v157
	v_and_b32_e32 v158, s10, v158
	v_and_b32_e32 v159, s10, v159
	v_and_b32_e32 v160, s10, v160
	v_and_b32_e32 v161, s10, v161
	v_mul_f32_e32 v76, v56, v56
	v_mul_f32_e32 v77, v57, v57
	v_mul_f32_e32 v78, v58, v58
	v_mul_f32_e32 v79, v59, v59
	v_fmac_f32_e32 v76, v146, v146
	v_fmac_f32_e32 v77, v147, v147
	v_fmac_f32_e32 v78, v148, v148
	v_fmac_f32_e32 v79, v149, v149
	v_fmac_f32_e32 v76, v60, v60
	v_fmac_f32_e32 v77, v61, v61
	v_fmac_f32_e32 v78, v62, v62
	v_fmac_f32_e32 v79, v63, v63
	v_fmac_f32_e32 v76, v64, v64
	v_fmac_f32_e32 v77, v65, v65
	v_fmac_f32_e32 v78, v66, v66
	v_fmac_f32_e32 v79, v67, v67
	v_fmac_f32_e32 v76, v68, v68
	v_fmac_f32_e32 v77, v69, v69
	v_fmac_f32_e32 v78, v70, v70
	v_fmac_f32_e32 v79, v71, v71
	v_fmac_f32_e32 v76, v150, v150
	v_fmac_f32_e32 v77, v151, v151
	v_fmac_f32_e32 v78, v152, v152
	v_fmac_f32_e32 v79, v153, v153
	v_fmac_f32_e32 v76, v154, v154
	v_fmac_f32_e32 v77, v155, v155
	v_fmac_f32_e32 v78, v156, v156
	v_fmac_f32_e32 v79, v157, v157
	v_fmac_f32_e32 v76, v158, v158
	v_fmac_f32_e32 v77, v159, v159
	v_fmac_f32_e32 v78, v160, v160
	v_fmac_f32_e32 v79, v161, v161
	v_add_f32_e32 v76, v76, v77
	v_add_f32_e32 v78, v78, v79
	s_nop 0
	v_add_f32_e32 v76, v76, v78
	s_nop 1
	v_add_f32_dpp v73, v72, v72 quad_perm:[1,0,3,2] row_mask:0xf bank_mask:0xf
	v_add_f32_dpp v77, v76, v76 quad_perm:[1,0,3,2] row_mask:0xf bank_mask:0xf
	s_nop 0
	v_add_f32_dpp v72, v73, v73 quad_perm:[2,3,0,1] row_mask:0xf bank_mask:0xf
	v_add_f32_dpp v76, v77, v77 quad_perm:[2,3,0,1] row_mask:0xf bank_mask:0xf
	s_nop 0
	v_add_f32_dpp v73, v72, v72 row_half_mirror row_mask:0xf bank_mask:0xf
	v_add_f32_dpp v77, v76, v76 row_half_mirror row_mask:0xf bank_mask:0xf
	s_nop 0
	v_add_f32_dpp v72, v73, v73 row_mirror row_mask:0xf bank_mask:0xf
	v_add_f32_dpp v76, v77, v77 row_mirror row_mask:0xf bank_mask:0xf
	s_nop 0
	v_fmamk_f32 v72, v72, 0x3b000000, v190
	v_fmamk_f32 v76, v76, 0x3b000000, v190
	v_cmp_gt_f32_e32 vcc, s96, v72
	v_cmp_gt_f32_e64 s[8:9], s96, v76
	v_mul_f32_e32 v73, 0x4b800000, v72
	v_mul_f32_e32 v77, 0x4b800000, v76
	v_cndmask_b32_e32 v72, v72, v73, vcc
	v_cndmask_b32_e64 v76, v76, v77, s[8:9]
	v_rsq_f32_e32 v72, v72
	v_rsq_f32_e32 v76, v76
	s_nop 0
	v_mul_f32_e32 v73, 0x45800000, v72
	v_mul_f32_e32 v77, 0x45800000, v76
	v_cndmask_b32_e32 v72, v72, v73, vcc
	v_cndmask_b32_e64 v76, v76, v77, s[8:9]
	v_mul_f32_e32 v40, v72, v40
	v_mul_f32_e32 v41, v72, v41
	v_mul_f32_e32 v42, v72, v42
	v_mul_f32_e32 v43, v72, v43
	v_mul_f32_e32 v44, v72, v44
	v_mul_f32_e32 v45, v72, v45
	v_mul_f32_e32 v46, v72, v46
	v_mul_f32_e32 v47, v72, v47
	v_mul_f32_e32 v48, v72, v48
	v_mul_f32_e32 v49, v72, v49
	v_mul_f32_e32 v50, v72, v50
	v_mul_f32_e32 v51, v72, v51
	v_mul_f32_e32 v52, v72, v52
	v_mul_f32_e32 v53, v72, v53
	v_mul_f32_e32 v54, v72, v54
	v_mul_f32_e32 v55, v72, v55
	v_mul_f32_e32 v130, v72, v130
	v_mul_f32_e32 v131, v72, v131
	v_mul_f32_e32 v132, v72, v132
	v_mul_f32_e32 v133, v72, v133
	v_mul_f32_e32 v134, v72, v134
	v_mul_f32_e32 v135, v72, v135
	v_mul_f32_e32 v136, v72, v136
	v_mul_f32_e32 v137, v72, v137
	v_mul_f32_e32 v138, v72, v138
	v_mul_f32_e32 v139, v72, v139
	v_mul_f32_e32 v140, v72, v140
	v_mul_f32_e32 v141, v72, v141
	v_mul_f32_e32 v142, v72, v142
	v_mul_f32_e32 v143, v72, v143
	v_mul_f32_e32 v144, v72, v144
	v_mul_f32_e32 v145, v72, v145
	v_cvt_pk_bf16_f32 v130, v40, v130
	v_cvt_pk_bf16_f32 v131, v41, v131
	v_cvt_pk_bf16_f32 v132, v42, v132
	v_cvt_pk_bf16_f32 v133, v43, v133
	v_cvt_pk_bf16_f32 v134, v44, v134
	v_cvt_pk_bf16_f32 v135, v45, v135
	v_cvt_pk_bf16_f32 v136, v46, v136
	v_cvt_pk_bf16_f32 v137, v47, v137
	v_cvt_pk_bf16_f32 v138, v48, v138
	v_cvt_pk_bf16_f32 v139, v49, v139
	v_cvt_pk_bf16_f32 v140, v50, v140
	v_cvt_pk_bf16_f32 v141, v51, v141
	v_cvt_pk_bf16_f32 v142, v52, v142
	v_cvt_pk_bf16_f32 v143, v53, v143
	v_cvt_pk_bf16_f32 v144, v54, v144
	v_cvt_pk_bf16_f32 v145, v55, v145
	v_mul_f32_e32 v56, v76, v56
	v_mul_f32_e32 v57, v76, v57
	v_mul_f32_e32 v58, v76, v58
	v_mul_f32_e32 v59, v76, v59
	v_mul_f32_e32 v60, v76, v60
	v_mul_f32_e32 v61, v76, v61
	v_mul_f32_e32 v62, v76, v62
	v_mul_f32_e32 v63, v76, v63
	v_mul_f32_e32 v64, v76, v64
	v_mul_f32_e32 v65, v76, v65
	v_mul_f32_e32 v66, v76, v66
	v_mul_f32_e32 v67, v76, v67
	v_mul_f32_e32 v68, v76, v68
	v_mul_f32_e32 v69, v76, v69
	v_mul_f32_e32 v70, v76, v70
	v_mul_f32_e32 v71, v76, v71
	v_mul_f32_e32 v146, v76, v146
	v_mul_f32_e32 v147, v76, v147
	v_mul_f32_e32 v148, v76, v148
	v_mul_f32_e32 v149, v76, v149
	v_mul_f32_e32 v150, v76, v150
	v_mul_f32_e32 v151, v76, v151
	v_mul_f32_e32 v152, v76, v152
	v_mul_f32_e32 v153, v76, v153
	v_mul_f32_e32 v154, v76, v154
	v_mul_f32_e32 v155, v76, v155
	v_mul_f32_e32 v156, v76, v156
	v_mul_f32_e32 v157, v76, v157
	v_mul_f32_e32 v158, v76, v158
	v_mul_f32_e32 v159, v76, v159
	v_mul_f32_e32 v160, v76, v160
	v_mul_f32_e32 v161, v76, v161
	v_cvt_pk_bf16_f32 v146, v56, v146
	v_cvt_pk_bf16_f32 v147, v57, v147
	v_cvt_pk_bf16_f32 v148, v58, v148
	v_cvt_pk_bf16_f32 v149, v59, v149
	v_cvt_pk_bf16_f32 v150, v60, v150
	v_cvt_pk_bf16_f32 v151, v61, v151
	v_cvt_pk_bf16_f32 v152, v62, v152
	v_cvt_pk_bf16_f32 v153, v63, v153
	v_cvt_pk_bf16_f32 v154, v64, v154
	v_cvt_pk_bf16_f32 v155, v65, v155
	v_cvt_pk_bf16_f32 v156, v66, v156
	v_cvt_pk_bf16_f32 v157, v67, v157
	v_cvt_pk_bf16_f32 v158, v68, v158
	v_cvt_pk_bf16_f32 v159, v69, v159
	v_cvt_pk_bf16_f32 v160, v70, v160
	v_cvt_pk_bf16_f32 v161, v71, v161
	global_store_dwordx4 v5, v[130:133], s[6:7]
	global_store_dwordx4 v5, v[134:137], s[6:7] offset:256
	global_store_dwordx4 v5, v[138:141], s[6:7] offset:512
	global_store_dwordx4 v5, v[142:145], s[6:7] offset:768
	global_store_dwordx4 v7, v[146:149], s[6:7]
	global_store_dwordx4 v7, v[150:153], s[6:7] offset:256
	global_store_dwordx4 v7, v[154:157], s[6:7] offset:512
	global_store_dwordx4 v7, v[158:161], s[6:7] offset:768
	s_waitcnt lgkmcnt(0)
	s_add_i32 s57, s57, s81
	v_readlane_b32 s6, v255, 31
	s_cmp_ge_i32 s57, s6
	s_barrier
	s_cbranch_scc0 .LBB0_268

.LBB0_571:
	s_nor_b64 s[8:9], vcc, s[4:5]
	s_and_saveexec_b64 s[4:5], s[8:9]
	s_cbranch_execz .LBB0_578
	s_load_dwordx2 s[16:17], s[0:1], 0x8
	s_load_dwordx2 s[10:11], s[0:1], 0x18
	s_waitcnt lgkmcnt(0)
	global_load_dword v2, v57, s[16:17]
	global_load_dword v3, v57, s[16:17] offset:2048
	s_add_u32 s16, s16, 0x1000
	s_addc_u32 s17, s17, 0
	global_load_dword v4, v57, s[16:17]
	global_load_dword v5, v57, s[16:17] offset:2048
	s_add_u32 s16, s16, 0x1000
	s_addc_u32 s17, s17, 0
	global_load_dword v6, v57, s[16:17]
	global_load_dword v7, v57, s[16:17] offset:2048
	s_add_u32 s16, s16, 0x1000
	s_addc_u32 s17, s17, 0
	global_load_dword v8, v57, s[16:17]
	global_load_dword v9, v57, s[16:17] offset:2048
	global_load_dword v10, v57, s[10:11]
	global_load_dword v11, v57, s[10:11] offset:2048
	s_waitcnt vmcnt(9)
	v_mul_f32_e32 v12, 0xbfb8aa3b, v2
	v_exp_f32_e32 v12, v12
	s_waitcnt vmcnt(8)
	v_mul_f32_e32 v13, 0xbfb8aa3b, v3
	v_exp_f32_e32 v13, v13
	s_waitcnt vmcnt(7)
	v_mul_f32_e32 v14, 0xbfb8aa3b, v4
	v_exp_f32_e32 v14, v14
	s_waitcnt vmcnt(6)
	v_mul_f32_e32 v15, 0xbfb8aa3b, v5
	v_exp_f32_e32 v15, v15
	s_waitcnt vmcnt(5)
	v_mul_f32_e32 v16, 0xbfb8aa3b, v6
	v_exp_f32_e32 v16, v16
	s_waitcnt vmcnt(4)
	v_mul_f32_e32 v17, 0xbfb8aa3b, v7
	v_exp_f32_e32 v17, v17
	s_waitcnt vmcnt(3)
	v_mul_f32_e32 v18, 0xbfb8aa3b, v8
	v_exp_f32_e32 v18, v18
	s_waitcnt vmcnt(2)
	v_mul_f32_e32 v19, 0xbfb8aa3b, v9
	v_exp_f32_e32 v19, v19
	s_waitcnt vmcnt(1)
	v_mul_f32_e32 v20, 0xbfb8aa3b, v10
	v_exp_f32_e32 v20, v20
	s_waitcnt vmcnt(0)
	v_mul_f32_e32 v21, 0xbfb8aa3b, v11
	v_exp_f32_e32 v21, v21
	v_add_f32_e32 v12, 1.0, v12
	v_add_f32_e32 v13, 1.0, v13
	v_add_f32_e32 v14, 1.0, v14
	v_add_f32_e32 v15, 1.0, v15
	v_add_f32_e32 v16, 1.0, v16
	v_add_f32_e32 v17, 1.0, v17
	v_add_f32_e32 v18, 1.0, v18
	v_add_f32_e32 v19, 1.0, v19
	v_add_f32_e32 v20, 1.0, v20
	v_add_f32_e32 v21, 1.0, v21
	v_rcp_f32_e32 v12, v12
	v_rcp_f32_e32 v13, v13
	v_rcp_f32_e32 v14, v14
	v_rcp_f32_e32 v15, v15
	v_rcp_f32_e32 v16, v16
	v_rcp_f32_e32 v17, v17
	v_rcp_f32_e32 v18, v18
	v_rcp_f32_e32 v19, v19
	v_rcp_f32_e32 v20, v20
	v_rcp_f32_e32 v21, v21
	v_mul_f32_e32 v2, v2, v12
	v_mul_f32_e32 v3, v3, v13
	v_mul_f32_e32 v4, v4, v14
	v_mul_f32_e32 v5, v5, v15
	v_mul_f32_e32 v6, v6, v16
	v_mul_f32_e32 v7, v7, v17
	v_mul_f32_e32 v8, v8, v18
	v_mul_f32_e32 v9, v9, v19
	v_mul_f32_e32 v10, v10, v20
	v_mul_f32_e32 v11, v11, v21
	ds_write_b32 v57, v2
	ds_write_b32 v57, v3 offset:2048
	ds_write_b32 v57, v4 offset:4096
	ds_write_b32 v57, v5 offset:6144
	ds_write_b32 v57, v6 offset:8192
	ds_write_b32 v57, v7 offset:10240
	ds_write_b32 v57, v8 offset:12288
	ds_write_b32 v57, v9 offset:14336
	ds_write_b32 v57, v10 offset:16384
	ds_write_b32 v57, v11 offset:18432
